# v35: v33 + 64-byte alignment of ten hot loop heads (attention, in-proj/merge GEMM K-loops, mLSTM chunk loop, FA/FB, qkprep, prenorm, mlstm_out)
# baseline (speedup 1.0000x reference)
.LBB0_170:
	s_or_b64 exec, exec, s[10:11]
	v_readlane_b32 s10, v254, 47
	v_readlane_b32 s11, v254, 48
	s_movk_i32 s6, 0x43ff
	v_add_u32_e32 v24, s10, v24
	v_readlane_b32 s10, v254, 45
	v_readlane_b32 s11, v254, 46
	v_cmp_lt_i32_e64 s[74:75], s6, v24
	s_or_b64 s[88:89], s[74:75], s[88:89]
	v_lshl_add_u64 v[30:31], v[30:31], 0, s[10:11]
	v_readlane_b32 s10, v254, 49
	v_readlane_b32 s11, v254, 50
	s_nop 1
	v_lshl_add_u64 v[32:33], v[32:33], 0, s[10:11]
	s_andn2_b64 exec, exec, s[88:89]
	s_cbranch_execz .LBB0_178
	.p2align 6

.LBB0_387:
	s_or_b64 exec, exec, s[14:15]
	v_readlane_b32 s14, v254, 47
	s_movk_i32 s6, 0x43ff
	s_nop 1
	v_cvt_pk_bf16_f32 v42, v42, v43
	s_nop 1
	v_cvt_pk_bf16_f32 v50, v50, v51
	s_nop 1
	v_cvt_pk_bf16_f32 v43, v44, v45
	s_nop 1
	v_cvt_pk_bf16_f32 v51, v52, v53
	s_nop 0
	v_add_u32_e32 v34, s14, v34
	v_cmp_lt_i32_e64 s[42:43], s6, v34
	s_or_b64 s[12:13], s[42:43], s[12:13]
	s_nop 1
	v_cvt_pk_bf16_f32 v44, v46, v47
	s_nop 1
	v_cvt_pk_bf16_f32 v52, v54, v55
	s_nop 1
	v_cvt_pk_bf16_f32 v45, v48, v49
	s_nop 1
	v_cvt_pk_bf16_f32 v53, v56, v57
	global_store_dwordx4 v[40:41], v[42:45], off
	v_readlane_b32 s15, v254, 48
	global_store_dwordx4 v[40:41], v[50:53], off offset:16
	s_andn2_b64 exec, exec, s[12:13]
	s_cbranch_execz .LBB0_392
	.p2align 6

.LBB0_469:
	s_and_b64 vcc, exec, s[14:15]
	s_cbranch_vccnz .LBB0_475
	.p2align 6

.LBB0_513:
	s_and_b64 vcc, exec, s[14:15]
	s_mov_b64 s[14:15], s[48:49]
	s_cbranch_vccnz .LBB0_519
	.p2align 6

.Lctxpub_done:
	.p2align 6

.LBB0_844:
	s_or_b64 exec, exec, s[10:11]
	s_waitcnt vmcnt(0)
	v_mov_b32_e32 v18, v232
	s_waitcnt vmcnt(0) lgkmcnt(0)
	s_barrier
	s_nop 0
	v_ashrrev_i32_e32 v19, 6, v18
	v_cmp_gt_i32_e32 vcc, 64, v19
	s_and_saveexec_b64 s[10:11], vcc
	s_mov_b64 s[36:37], 0x4000
	s_mov_b64 s[40:41], 0x2200000
	s_cbranch_execz .LBB0_847
	s_load_dwordx2 s[14:15], s[44:45], 0x48
	v_readlane_b32 s26, v255, 32
	v_lshlrev_b32_e32 v1, 6, v18
	v_readlane_b32 s27, v255, 33
	v_and_b32_e32 v1, 0xfc0, v1
	s_waitcnt lgkmcnt(0)
	s_add_u32 s14, s14, s26
	s_addc_u32 s15, s15, s27
	global_load_dwordx4 v[2:5], v1, s[14:15]
	global_load_dwordx4 v[6:9], v1, s[14:15] offset:16
	global_load_dwordx4 v[10:13], v1, s[14:15] offset:32
	global_load_dwordx4 v[14:17], v1, s[14:15] offset:48
	v_readlane_b32 s6, v255, 30
	s_sub_i32 s6, s62, s6
	s_lshr_b32 s14, s6, 6
	s_lshl_b32 s6, s6, 6
	s_mul_i32 s15, s14, 0x1100
	s_and_b32 s6, s6, 0xfc0
	v_cmp_lt_i32_e32 vcc, v231, v225
	s_add_i32 s14, s15, s6
	s_and_b32 s6, s62, 63
	v_cndmask_b32_e32 v1, v223, v231, vcc
	v_cmp_lt_i32_e32 vcc, v230, v225
	s_lshl_b32 s6, s6, 6
	s_add_i32 s6, s6, s15
	v_cndmask_b32_e32 v20, v223, v230, vcc
	v_cmp_lt_i32_e32 vcc, v229, v225
	v_lshlrev_b32_e32 v26, 2, v20
	s_load_dwordx2 s[26:27], s[44:45], 0xb0
	v_cndmask_b32_e32 v20, v223, v229, vcc
	v_cmp_lt_i32_e32 vcc, v222, v225
	v_lshlrev_b32_e32 v27, 2, v20
	v_add_u32_e32 v19, s6, v19
	v_cndmask_b32_e32 v20, v223, v222, vcc
	v_lshlrev_b32_e32 v28, 2, v20
	v_add_u32_e32 v20, 0x100, v19
	v_ashrrev_i32_e32 v21, 31, v20
	v_lshlrev_b64 v[20:21], 11, v[20:21]
	v_and_b32_e32 v18, 63, v18
	v_lshl_or_b32 v20, v18, 5, v20
	v_add_u32_e32 v29, 0xf8, v19
	s_waitcnt lgkmcnt(0)
	v_lshl_add_u64 v[18:19], s[26:27], 0, v[20:21]
	s_mov_b64 s[26:27], 0x25610000
	v_lshlrev_b32_e32 v1, 2, v1
	s_addk_i32 s14, 0x138
	v_lshl_add_u64 v[18:19], v[18:19], 0, s[26:27]
	s_mov_b64 s[26:27], 0
	v_lshl_add_u64 v[62:63], v[18:19], 0, s[40:41]
	global_load_dwordx4 v[100:103], v[18:19], off offset:16
	global_load_dwordx4 v[104:107], v[18:19], off
	global_load_dwordx4 v[108:111], v[62:63], off
	global_load_dwordx4 v[112:115], v[62:63], off offset:16
	v_add_co_u32_e32 v64, vcc, s92, v18
	s_nop 1
	v_addc_co_u32_e32 v65, vcc, -1, v19, vcc
	global_load_dwordx4 v[116:119], v[64:65], off
	v_add_co_u32_e32 v64, vcc, s93, v18
	s_nop 1
	v_addc_co_u32_e32 v65, vcc, -1, v19, vcc
	global_load_dwordx4 v[120:123], v[64:65], off
	v_add_co_u32_e32 v64, vcc, s94, v18
	s_nop 1
	v_addc_co_u32_e32 v65, vcc, -1, v19, vcc
	global_load_dwordx4 v[124:127], v[64:65], off offset:-4080
	v_add_co_u32_e32 v64, vcc, s95, v18
	s_nop 1
	v_addc_co_u32_e32 v65, vcc, -1, v19, vcc
	global_load_dwordx4 v[128:131], v[64:65], off offset:-4080
	s_waitcnt vmcnt(0)
	.p2align 6

.LBB0_914:
	s_add_u32 s10, s10, 0x40080
	s_addc_u32 s11, s11, 0
	s_add_u32 s44, s14, 0x100
	s_addc_u32 s45, s15, 0
	s_mov_b32 s55, -2
	.p2align 6

.LBB0_1102:
	s_add_u32 s48, s48, 0x40080
	s_addc_u32 s49, s49, 0
	s_add_u32 s6, s14, 0x100
	v_mov_b32_e32 v2, 0
	s_addc_u32 s37, s15, 0
	s_mov_b32 s43, -2
	v_mov_b32_e32 v3, v2
	v_mov_b32_e32 v4, v2
	v_mov_b32_e32 v5, v2
	v_mov_b32_e32 v6, v2
	v_mov_b32_e32 v7, v2
	v_mov_b32_e32 v8, v2
	v_mov_b32_e32 v9, v2
	v_mov_b32_e32 v10, v2
	v_mov_b32_e32 v11, v2
	v_mov_b32_e32 v12, v2
	v_mov_b32_e32 v13, v2
	v_mov_b32_e32 v22, v2
	v_mov_b32_e32 v23, v2
	v_mov_b32_e32 v24, v2
	v_mov_b32_e32 v25, v2
	v_mov_b32_e32 v26, v2
	v_mov_b32_e32 v27, v2
	v_mov_b32_e32 v28, v2
	v_mov_b32_e32 v29, v2
	v_mov_b32_e32 v38, v2
	v_mov_b32_e32 v39, v2
	v_mov_b32_e32 v40, v2
	v_mov_b32_e32 v41, v2
	v_mov_b32_e32 v42, v2
	v_mov_b32_e32 v43, v2
	v_mov_b32_e32 v44, v2
	v_mov_b32_e32 v45, v2
	v_mov_b32_e32 v54, v2
	v_mov_b32_e32 v55, v2
	v_mov_b32_e32 v56, v2
	v_mov_b32_e32 v57, v2
	v_mov_b32_e32 v14, v2
	v_mov_b32_e32 v15, v2
	v_mov_b32_e32 v16, v2
	v_mov_b32_e32 v17, v2
	v_mov_b32_e32 v18, v2
	v_mov_b32_e32 v19, v2
	v_mov_b32_e32 v20, v2
	v_mov_b32_e32 v21, v2
	v_mov_b32_e32 v30, v2
	v_mov_b32_e32 v31, v2
	v_mov_b32_e32 v32, v2
	v_mov_b32_e32 v33, v2
	v_mov_b32_e32 v34, v2
	v_mov_b32_e32 v35, v2
	v_mov_b32_e32 v36, v2
	v_mov_b32_e32 v37, v2
	v_mov_b32_e32 v46, v2
	v_mov_b32_e32 v47, v2
	v_mov_b32_e32 v48, v2
	v_mov_b32_e32 v49, v2
	v_mov_b32_e32 v50, v2
	v_mov_b32_e32 v51, v2
	v_mov_b32_e32 v52, v2
	v_mov_b32_e32 v53, v2
	v_mov_b32_e32 v58, v2
	v_mov_b32_e32 v59, v2
	v_mov_b32_e32 v60, v2
	v_mov_b32_e32 v61, v2
	v_mov_b32_e32 v62, v2
	v_mov_b32_e32 v63, v2
	v_mov_b32_e32 v64, v2
	v_mov_b32_e32 v65, v2
	v_mov_b32_e32 v66, v2
	v_mov_b32_e32 v67, v2
	v_mov_b32_e32 v68, v2
	v_mov_b32_e32 v69, v2
	v_mov_b32_e32 v70, v2
	v_mov_b32_e32 v71, v2
	v_mov_b32_e32 v72, v2
	v_mov_b32_e32 v73, v2
	v_mov_b32_e32 v74, v2
	v_mov_b32_e32 v75, v2
	v_mov_b32_e32 v76, v2
	v_mov_b32_e32 v77, v2
	v_mov_b32_e32 v86, v2
	v_mov_b32_e32 v87, v2
	v_mov_b32_e32 v88, v2
	v_mov_b32_e32 v89, v2
	v_mov_b32_e32 v90, v2
	v_mov_b32_e32 v91, v2
	v_mov_b32_e32 v92, v2
	v_mov_b32_e32 v93, v2
	v_mov_b32_e32 v102, v2
	v_mov_b32_e32 v103, v2
	v_mov_b32_e32 v104, v2
	v_mov_b32_e32 v105, v2
	v_mov_b32_e32 v106, v2
	v_mov_b32_e32 v107, v2
	v_mov_b32_e32 v108, v2
	v_mov_b32_e32 v109, v2
	v_mov_b32_e32 v118, v2
	v_mov_b32_e32 v119, v2
	v_mov_b32_e32 v120, v2
	v_mov_b32_e32 v121, v2
	v_mov_b32_e32 v78, v2
	v_mov_b32_e32 v79, v2
	v_mov_b32_e32 v80, v2
	v_mov_b32_e32 v81, v2
	v_mov_b32_e32 v82, v2
	v_mov_b32_e32 v83, v2
	v_mov_b32_e32 v84, v2
	v_mov_b32_e32 v85, v2
	v_mov_b32_e32 v94, v2
	v_mov_b32_e32 v95, v2
	v_mov_b32_e32 v96, v2
	v_mov_b32_e32 v97, v2
	v_mov_b32_e32 v98, v2
	v_mov_b32_e32 v99, v2
	v_mov_b32_e32 v100, v2
	v_mov_b32_e32 v101, v2
	v_mov_b32_e32 v110, v2
	v_mov_b32_e32 v111, v2
	v_mov_b32_e32 v112, v2
	v_mov_b32_e32 v113, v2
	v_mov_b32_e32 v114, v2
	v_mov_b32_e32 v115, v2
	v_mov_b32_e32 v116, v2
	v_mov_b32_e32 v117, v2
	v_mov_b32_e32 v122, v2
	v_mov_b32_e32 v123, v2
	v_mov_b32_e32 v124, v2
	v_mov_b32_e32 v125, v2
	v_mov_b32_e32 v126, v2
	v_mov_b32_e32 v127, v2
	v_mov_b32_e32 v128, v2
	v_mov_b32_e32 v129, v2
	.p2align 6
